# v55_nt
# speedup vs baseline: 1.0105x; 1.0085x over previous
; DI float wave_sum(float v, int lane) {
; #pragma unroll
;     for (int o = 1; o < 64; o <<= 1) v += __uint_as_float((unsigned)__builtin_amdgcn_ds_bpermute((lane ^ o) << 2, (int)__float_as_uint(v)));
;     return v;
; }
; DI void rms_row_f32(float* xrow, const float* gam, int lane) {
;     f32x4 v[8]; float ss = 0.f;
; #pragma unroll
;     for (int j = 0; j < 8; ++j) { v[j] = ((const f32x4*)xrow)[lane + 64 * j]; ss += (v[j].x * v[j].x + v[j].y * v[j].y) + (v[j].z * v[j].z + v[j].w * v[j].w); }
;     const float rinv = rsqrtf(wave_sum(ss, lane) * (1.f / DM) + 1e-6f);
; #pragma unroll
;     for (int j = 0; j < 8; ++j) { const f32x4 g = ((const f32x4*)gam)[lane + 64 * j]; ((f32x4*)xrow)[lane + 64 * j] = v[j] * rinv * g; }
; }
.Lrms_c_nopf:
	v_mul_f32_e32 v177, v64, v64
	v_mul_f32_e32 v178, v66, v66
	v_fmac_f32_e32 v177, v65, v65
	v_fmac_f32_e32 v178, v67, v67
	v_add_f32_e32 v176, v177, v178
	v_mul_f32_e32 v177, v68, v68
	v_mul_f32_e32 v178, v70, v70
	v_fmac_f32_e32 v177, v69, v69
	v_fmac_f32_e32 v178, v71, v71
	v_add_f32_e32 v177, v177, v178
	v_add_f32_e32 v176, v176, v177
	v_mul_f32_e32 v177, v72, v72
	v_mul_f32_e32 v178, v74, v74
	v_fmac_f32_e32 v177, v73, v73
	v_fmac_f32_e32 v178, v75, v75
	v_add_f32_e32 v177, v177, v178
	v_add_f32_e32 v176, v176, v177
	v_mul_f32_e32 v177, v76, v76
	v_mul_f32_e32 v178, v78, v78
	v_fmac_f32_e32 v177, v77, v77
	v_fmac_f32_e32 v178, v79, v79
	v_add_f32_e32 v177, v177, v178
	v_add_f32_e32 v176, v176, v177
	v_mul_f32_e32 v177, v80, v80
	v_mul_f32_e32 v178, v82, v82
	v_fmac_f32_e32 v177, v81, v81
	v_fmac_f32_e32 v178, v83, v83
	v_add_f32_e32 v177, v177, v178
	v_add_f32_e32 v176, v176, v177
	v_mul_f32_e32 v177, v84, v84
	v_mul_f32_e32 v178, v86, v86
	v_fmac_f32_e32 v177, v85, v85
	v_fmac_f32_e32 v178, v87, v87
	v_add_f32_e32 v177, v177, v178
	v_add_f32_e32 v176, v176, v177
	v_mul_f32_e32 v177, v88, v88
	v_mul_f32_e32 v178, v90, v90
	v_fmac_f32_e32 v177, v89, v89
	v_fmac_f32_e32 v178, v91, v91
	v_add_f32_e32 v177, v177, v178
	v_add_f32_e32 v176, v176, v177
	v_mul_f32_e32 v177, v92, v92
	v_mul_f32_e32 v178, v94, v94
	v_fmac_f32_e32 v177, v93, v93
	v_fmac_f32_e32 v178, v95, v95
	v_add_f32_e32 v177, v177, v178
	v_add_f32_e32 v176, v176, v177
	ds_bpermute_b32 v179, v0, v176
	s_waitcnt lgkmcnt(0)
	v_add_f32_e32 v176, v176, v179
	ds_bpermute_b32 v179, v18, v176
	s_waitcnt lgkmcnt(0)
	v_add_f32_e32 v176, v176, v179
	ds_bpermute_b32 v179, v19, v176
	s_waitcnt lgkmcnt(0)
	v_add_f32_e32 v176, v176, v179
	ds_bpermute_b32 v179, v20, v176
	s_waitcnt lgkmcnt(0)
	v_add_f32_e32 v176, v176, v179
	ds_bpermute_b32 v179, v21, v176
	s_waitcnt lgkmcnt(0)
	v_add_f32_e32 v176, v176, v179
	ds_bpermute_b32 v179, v22, v176
	s_waitcnt lgkmcnt(0)
	v_add_f32_e32 v176, v176, v179
	v_fmamk_f32 v176, v176, 0x3a000000, v230
	v_mul_f32_e32 v179, 0x4b800000, v176
	v_cmp_gt_f32_e32 vcc, s29, v176
	s_nop 1
	v_cndmask_b32_e32 v176, v176, v179, vcc
	v_rsq_f32_e32 v176, v176
	s_nop 0
	v_mul_f32_e32 v179, 0x45800000, v176
	v_cndmask_b32_e32 v180, v176, v179, vcc
	v_pk_mul_f32 v[64:65], v[64:65], v[180:181] op_sel_hi:[1,0]
	v_pk_mul_f32 v[66:67], v[66:67], v[180:181] op_sel_hi:[1,0]
	v_pk_mul_f32 v[64:65], v[128:129], v[64:65]
	v_pk_mul_f32 v[66:67], v[130:131], v[66:67]
	global_store_dwordx4 v[60:61], v[64:67], off offset:-4096 nt
	v_pk_mul_f32 v[68:69], v[68:69], v[180:181] op_sel_hi:[1,0]
	v_pk_mul_f32 v[70:71], v[70:71], v[180:181] op_sel_hi:[1,0]
	v_pk_mul_f32 v[68:69], v[132:133], v[68:69]
	v_pk_mul_f32 v[70:71], v[134:135], v[70:71]
	global_store_dwordx4 v[60:61], v[68:71], off offset:-3072 nt
	v_pk_mul_f32 v[72:73], v[72:73], v[180:181] op_sel_hi:[1,0]
	v_pk_mul_f32 v[74:75], v[74:75], v[180:181] op_sel_hi:[1,0]
	v_pk_mul_f32 v[72:73], v[136:137], v[72:73]
	v_pk_mul_f32 v[74:75], v[138:139], v[74:75]
	global_store_dwordx4 v[60:61], v[72:75], off offset:-2048 nt
	v_pk_mul_f32 v[76:77], v[76:77], v[180:181] op_sel_hi:[1,0]
	v_pk_mul_f32 v[78:79], v[78:79], v[180:181] op_sel_hi:[1,0]
	v_pk_mul_f32 v[76:77], v[140:141], v[76:77]
	v_pk_mul_f32 v[78:79], v[142:143], v[78:79]
	global_store_dwordx4 v[60:61], v[76:79], off offset:-1024 nt
	v_pk_mul_f32 v[80:81], v[80:81], v[180:181] op_sel_hi:[1,0]
	v_pk_mul_f32 v[82:83], v[82:83], v[180:181] op_sel_hi:[1,0]
	v_pk_mul_f32 v[80:81], v[144:145], v[80:81]
	v_pk_mul_f32 v[82:83], v[146:147], v[82:83]
	global_store_dwordx4 v[60:61], v[80:83], off offset:0 nt
	v_pk_mul_f32 v[84:85], v[84:85], v[180:181] op_sel_hi:[1,0]
	v_pk_mul_f32 v[86:87], v[86:87], v[180:181] op_sel_hi:[1,0]
	v_pk_mul_f32 v[84:85], v[148:149], v[84:85]
	v_pk_mul_f32 v[86:87], v[150:151], v[86:87]
	global_store_dwordx4 v[60:61], v[84:87], off offset:1024 nt
	v_pk_mul_f32 v[88:89], v[88:89], v[180:181] op_sel_hi:[1,0]
	v_pk_mul_f32 v[90:91], v[90:91], v[180:181] op_sel_hi:[1,0]
	v_pk_mul_f32 v[88:89], v[152:153], v[88:89]
	v_pk_mul_f32 v[90:91], v[154:155], v[90:91]
	global_store_dwordx4 v[60:61], v[88:91], off offset:2048 nt
	v_pk_mul_f32 v[92:93], v[92:93], v[180:181] op_sel_hi:[1,0]
	v_pk_mul_f32 v[94:95], v[94:95], v[180:181] op_sel_hi:[1,0]
	v_pk_mul_f32 v[92:93], v[156:157], v[92:93]
	v_pk_mul_f32 v[94:95], v[158:159], v[94:95]
	global_store_dwordx4 v[60:61], v[92:95], off offset:3072 nt
	v_lshl_add_u64 v[60:61], v[60:61], 0, s[60:61]
	s_cmpk_gt_i32 s6, 0x3fff
	s_cbranch_scc0 .Lrms_c_loop
